# rwkv_post per-head loop issues its first two loads before the workgroup barrier
# baseline (speedup 1.0000x reference)
; #define LAS __attribute__((address_space(3)))
; __device__ __forceinline__ float bf_lo(unsigned w) { return __uint_as_float(w << 16); }
; __device__ __forceinline__ float bf_hi(unsigned w) { return __uint_as_float(w & 0xffff0000u); }
; __device__ void rwkv_post_phase(const Params& p, int l, LAS unsigned char* lds) {
;     ...
;                 __syncthreads();
; #pragma unroll
;                 for (int i = 0; i < 2; ++i) { const int id = wid + 8 * i, rt = id >> 2, ct = id & 3; const f32x4 z4 = {0.f, 0.f, 0.f, 0.f};
;                     const f32x4 acc = mm_nt<3>(sgb + tl * 6656, 104, rt * 16, g2T + h * 64 * 104, 104, ct * 16, r16, quad, z4);
; #pragma unroll
;                     for (int j = 0; j < 4; ++j) gs[(rt * 16 + quad * 4 + j) * 64 + ct * 16 + r16] = acc[j]; }
;                 __syncthreads();
;                 const f32x4 gA = *(const LAS f32x4*)(gs + tp * 64 + cg * 4), gB = *(const LAS f32x4*)(gs + (tp + 32) * 64 + cg * 4);
; #pragma unroll
;                 for (int which = 0; which < 2; ++which) {
;                     const size_t t = t0 + tp + which * 32; const int s = (int)(t & (SEQ_ - 1));
;                     const u32x2 yfr = *(const u32x2*)(YF + t * 512 + c), ybr = *(const u32x2*)(YBk + t * 512 + c);
;                     f32x4 y; y[0] = bf_lo(yfr.x) + bf_lo(ybr.x); y[1] = bf_hi(yfr.x) + bf_hi(ybr.x); y[2] = bf_lo(yfr.y) + bf_lo(ybr.y); y[3] = bf_hi(yfr.y) + bf_hi(ybr.y);
;                     const float mean = red16d(y[0] + y[1] + y[2] + y[3]) * (1.0f / 64.0f);
;                     const f32x4 d = y - mean;
;                     const float var = red16d(d[0] * d[0] + d[1] * d[1] + d[2] * d[2] + d[3] * d[3]) * (1.0f / 64.0f);
;                     const float rs = rsqrtf(var + 64e-5f);
;                     const bf16_t* zp = ZR + t * ZRC + 1024 + c;
;                     const u32x2 vc = *(const u32x2*)zp; u32x2 vp = {0u, 0u}, vn = {0u, 0u};
;                     if (s > 0) vp = *(const u32x2*)(zp - ZRC);
;                     if (s < SEQ_ - 1) vn = *(const u32x2*)(zp + ZRC);
.LBB0_215:
	s_mov_b32 s20, s39
	s_waitcnt lgkmcnt(0)
	s_barrier
	ds_read_b128 v[14:17], v57
	ds_read_b128 v[18:21], v27
	s_waitcnt lgkmcnt(0)
	v_mfma_f32_16x16x32_bf16 v[14:17], v[14:17], v[18:21], 0
	ds_read_b128 v[18:21], v57 offset:64
	ds_read_b128 v[32:35], v27 offset:64
	v_add_u32_e32 v0, v51, v53
	s_mul_i32 s20, s20, s22
	s_waitcnt lgkmcnt(0)
	v_mfma_f32_16x16x32_bf16 v[14:17], v[18:21], v[32:35], v[14:17]
	ds_read_b128 v[18:21], v57 offset:128
	ds_read_b128 v[32:35], v27 offset:128
	s_add_i32 s20, s20, s34
	s_ashr_i32 s21, s20, 31
	s_waitcnt lgkmcnt(0)
	v_mfma_f32_16x16x32_bf16 v[14:17], v[18:21], v[32:35], v[14:17]
	s_nop 7
	ds_write2st64_b32 v0, v14, v15 offset1:1
	ds_write2st64_b32 v0, v16, v17 offset0:2 offset1:3
	ds_read_b128 v[14:17], v57 offset:6656
	ds_read_b128 v[18:21], v27
	s_waitcnt lgkmcnt(0)
	v_mfma_f32_16x16x32_bf16 v[14:17], v[14:17], v[18:21], 0
	ds_read_b128 v[18:21], v57 offset:6720
	ds_read_b128 v[32:35], v27 offset:64
	s_lshl_b64 s[20:21], s[20:21], 6
	v_mov_b32_e32 v42, 0
	s_waitcnt lgkmcnt(0)
	v_mfma_f32_16x16x32_bf16 v[14:17], v[18:21], v[32:35], v[14:17]
	ds_read_b128 v[18:21], v57 offset:6784
	ds_read_b128 v[32:35], v27 offset:128
	v_mov_b32_e32 v48, 0
	v_mov_b32_e32 v49, 0
	s_waitcnt lgkmcnt(0)
	v_mfma_f32_16x16x32_bf16 v[14:17], v[18:21], v[32:35], v[14:17]
	v_lshl_add_u64 v[34:35], s[20:21], 0, v[24:25]
	v_lshlrev_b64 v[32:33], 10, v[34:35]
	v_lshl_add_u64 v[36:37], v[28:29], 0, v[32:33]
	v_lshl_add_u64 v[32:33], v[30:31], 0, v[32:33]
	global_load_dwordx2 v[40:41], v[36:37], off
	global_load_dwordx2 v[32:33], v[32:33], off
	s_nop 3
	ds_write2st64_b32 v56, v14, v15 offset1:1
	ds_write2st64_b32 v56, v16, v17 offset0:2 offset1:3
	s_waitcnt lgkmcnt(0)
	s_barrier
	ds_read_b128 v[18:21], v52
	ds_read_b128 v[14:17], v52 offset:8192
	v_and_b32_e32 v43, 0x7ff, v34
	v_cmp_ne_u32_e32 vcc, 0, v43
	s_waitcnt vmcnt(0) lgkmcnt(0)
	v_lshlrev_b32_e32 v38, 16, v40
	v_and_b32_e32 v39, 0xffff0000, v40
	v_lshlrev_b32_e32 v44, 16, v32
	v_and_b32_e32 v45, 0xffff0000, v32
	v_pk_add_f32 v[38:39], v[38:39], v[44:45]
	v_lshlrev_b32_e32 v40, 16, v41
	v_and_b32_e32 v41, 0xffff0000, v41
	v_lshlrev_b32_e32 v32, 16, v33
	v_and_b32_e32 v33, 0xffff0000, v33
	v_pk_add_f32 v[40:41], v[40:41], v[32:33]
	v_add_f32_e32 v0, v38, v39
	v_add_f32_e32 v0, v40, v0
	v_add_f32_e32 v0, v41, v0
	s_nop 1
	v_add_f32_dpp v0, v0, v0 quad_perm:[1,0,3,2] row_mask:0xf bank_mask:0xf bound_ctrl:1
	s_nop 1
	v_add_f32_dpp v0, v0, v0 quad_perm:[2,3,0,1] row_mask:0xf bank_mask:0xf bound_ctrl:1
	s_nop 1
	v_add_f32_dpp v0, v0, v0 row_half_mirror row_mask:0xf bank_mask:0xf bound_ctrl:1
	s_nop 1
	v_add_f32_dpp v0, v0, v0 row_mirror row_mask:0xf bank_mask:0xf bound_ctrl:1
	v_fmamk_f32 v39, v0, 0xbc800000, v39
	v_fmac_f32_e32 v38, 0xbc800000, v0
	v_fmamk_f32 v41, v0, 0xbc800000, v41
	v_fmac_f32_e32 v40, 0xbc800000, v0
	v_pk_mul_f32 v[44:45], v[38:39], v[38:39]
	v_pk_mul_f32 v[32:33], v[40:41], v[40:41]
	v_add_f32_e32 v0, v44, v45
	v_add_f32_e32 v0, v32, v0
	v_add_f32_e32 v0, v33, v0
	v_mov_b64_e32 v[32:33], s[4:5]
	v_mad_u64_u32 v[32:33], s[20:21], v34, s46, v[32:33]
	v_add_f32_dpp v0, v0, v0 quad_perm:[1,0,3,2] row_mask:0xf bank_mask:0xf bound_ctrl:1
	v_mad_i32_i24 v33, v35, s46, v33
	s_nop 0
	v_add_f32_dpp v0, v0, v0 quad_perm:[2,3,0,1] row_mask:0xf bank_mask:0xf bound_ctrl:1
	s_nop 1
	v_add_f32_dpp v58, v0, v0 row_half_mirror row_mask:0xf bank_mask:0xf bound_ctrl:1
	v_lshlrev_b32_e32 v0, 1, v26
	v_lshl_add_u64 v[44:45], v[32:33], 0, v[0:1]
	v_lshl_add_u64 v[46:47], v[44:45], 0, s[36:37]
	flat_load_dwordx2 v[44:45], v[44:45] offset:2048
	v_mov_b32_dpp v59, v58 row_mirror row_mask:0xf bank_mask:0xf bound_ctrl:1
	s_and_saveexec_b64 s[20:21], vcc
	s_cbranch_execz .LBB0_217
	v_add_co_u32_e32 v48, vcc, 0xfffff240, v46
	s_nop 1
	v_addc_co_u32_e32 v49, vcc, -1, v47, vcc
	flat_load_dwordx2 v[48:49], v[48:49]
